# MODE_UP epilogue: packed outputs lane-transposed with ds_bpermute so each lane quad stores one row's 64 contiguous bytes (coalesced stores)
# speedup vs baseline: 1.0169x; 1.0169x over previous
; __device__ __forceinline__ float sigm(float v) { return __builtin_amdgcn_rcpf(1.0f + __builtin_amdgcn_exp2f(-1.44269504089f * v)); }
; __device__ __forceinline__ u32x4 pack8(const f32x4& v0, const f32x4& v1) { u32x4 w; w.x = cvt_pk_bf16(v0[0], v0[1]); w.y = cvt_pk_bf16(v0[2], v0[3]); w.z = cvt_pk_bf16(v1[0], v1[1]); w.w = cvt_pk_bf16(v1[2], v1[3]); return w; }
; __device__ __forceinline__ float sumsq8(const f32x4& v0, const f32x4& v1) { return (v0[0] * v0[0] + v0[1] * v0[1]) + (v0[2] * v0[2] + v0[3] * v0[3]) + (v1[0] * v1[0] + v1[1] * v1[1]) + (v1[2] * v1[2] + v1[3] * v1[3]); }
; template <int ACT> __device__ __forceinline__ void epi_act_store(f32x4 (&acc)[2][2][4][2], const float (&rs)[2][4], bf16_t* out, int ld, int row0, int col0, float* ssqv_slot, bool want_ssq, int fq) {
;     ...
;         for (int m = 0; m < 4; ++m) { const int row = row0 + ai * 128 + m * 16; float sq = 0.f;
; #pragma unroll
;             for (int bj = 0; bj < 2; ++bj) { f32x4 v0 = acc[ai][bj][m][0] * rs[ai][m], v1 = acc[ai][bj][m][1] * rs[ai][m];
;                 if (ACT == 1) { f32x2 a = gelu_pk((f32x2){v0[0], v0[1]}), b = gelu_pk((f32x2){v0[2], v0[3]}), c = gelu_pk((f32x2){v1[0], v1[1]}), d = gelu_pk((f32x2){v1[2], v1[3]});
;                     v0 = (f32x4){a.x, a.y, b.x, b.y}; v1 = (f32x4){c.x, c.y, d.x, d.y}; sq += sumsq8(v0, v1); }
;                 if (ACT == 2) {
; #pragma unroll
;                     for (int e = 0; e < 4; ++e) { v0[e] = sigm(v0[e]); v1[e] = sigm(v1[e]); } }
;                 *(u32x4*)(out + (size_t)row * ld + col0 + bj * 128) = pack8(v0, v1); }
; __device__ __forceinline__ void epi_run(const Epi& E, f32x4 (&acc)[2][2][4][2], const Unit& u, int wr, int wc, int fr, int fq) {
;     ...
;         if (mode == MODE_UP) { epi_act_store<0>(acc, rs, E.out16, E.ld16, row0, col0, nullptr, false, fq); return; }
.LBB0_349:
	s_andn2_b64 vcc, exec, s[8:9]
	s_cbranch_vccnz .LBB0_351
	s_waitcnt lgkmcnt(0)
	v_lshrrev_b32_e32 v214, 2, v201
	v_and_b32_e32 v215, 3, v201
	v_lshl_add_u32 v216, v215, 4, v214
	v_lshlrev_b32_e32 v216, 2, v216
	v_and_b32_e32 v217, -16, v239
	v_or_b32_e32 v217, v217, v214
	v_lshl_add_u32 v217, s95, 8, v217
	v_and_b32_e32 v218, 0xffffffe7, v242
	v_lshl_or_b32 v218, v215, 3, v218
	v_lshl_or_b32 v218, s23, 8, v218
	v_mul_lo_u32 v222, v217, s86
	v_add_u32_e32 v222, v222, v218
	v_mov_b32_e32 v223, 0
	v_lshl_add_u64 v[220:221], v[222:223], 1, s[70:71]
	s_lshl_b32 s8, s86, 5
	s_mov_b32 s9, 0
	s_mul_i32 s44, s86, 0xa0
	s_mov_b32 s45, 0
	v_pk_mul_f32 v[126:127], v[126:127], v[130:131] op_sel_hi:[1,0]
	v_pk_mul_f32 v[128:129], v[128:129], v[130:131] op_sel_hi:[1,0]
	v_pk_mul_f32 v[122:123], v[122:123], v[130:131] op_sel_hi:[1,0]
	v_pk_mul_f32 v[124:125], v[124:125], v[130:131] op_sel_hi:[1,0]
	v_cvt_pk_bf16_f32 v126, v126, v127
	v_cvt_pk_bf16_f32 v127, v128, v129
	v_cvt_pk_bf16_f32 v128, v122, v123
	v_cvt_pk_bf16_f32 v129, v124, v125
	ds_bpermute_b32 v224, v216, v126
	ds_bpermute_b32 v225, v216, v127
	ds_bpermute_b32 v226, v216, v128
	ds_bpermute_b32 v227, v216, v129
	v_pk_mul_f32 v[118:119], v[118:119], v[130:131] op_sel_hi:[1,0]
	v_pk_mul_f32 v[120:121], v[120:121], v[130:131] op_sel_hi:[1,0]
	v_pk_mul_f32 v[114:115], v[114:115], v[130:131] op_sel_hi:[1,0]
	v_pk_mul_f32 v[116:117], v[116:117], v[130:131] op_sel_hi:[1,0]
	v_cvt_pk_bf16_f32 v118, v118, v119
	v_cvt_pk_bf16_f32 v119, v120, v121
	v_cvt_pk_bf16_f32 v120, v114, v115
	v_cvt_pk_bf16_f32 v121, v116, v117
	ds_bpermute_b32 v228, v216, v118
	ds_bpermute_b32 v229, v216, v119
	ds_bpermute_b32 v230, v216, v120
	ds_bpermute_b32 v231, v216, v121
	s_waitcnt lgkmcnt(4)
	global_store_dwordx4 v[220:221], v[224:227], off
	v_pk_mul_f32 v[110:111], v[110:111], v[0:1] op_sel_hi:[1,0]
	v_pk_mul_f32 v[112:113], v[112:113], v[0:1] op_sel_hi:[1,0]
	v_pk_mul_f32 v[106:107], v[106:107], v[0:1] op_sel_hi:[1,0]
	v_pk_mul_f32 v[108:109], v[108:109], v[0:1] op_sel_hi:[1,0]
	v_cvt_pk_bf16_f32 v110, v110, v111
	v_cvt_pk_bf16_f32 v111, v112, v113
	v_cvt_pk_bf16_f32 v112, v106, v107
	v_cvt_pk_bf16_f32 v113, v108, v109
	ds_bpermute_b32 v224, v216, v110
	ds_bpermute_b32 v225, v216, v111
	ds_bpermute_b32 v226, v216, v112
	ds_bpermute_b32 v227, v216, v113
	s_waitcnt lgkmcnt(4)
	global_store_dwordx4 v[220:221], v[228:231], off offset:256
	v_lshl_add_u64 v[220:221], v[220:221], 0, s[8:9]
	v_pk_mul_f32 v[102:103], v[102:103], v[0:1] op_sel_hi:[1,0]
	v_pk_mul_f32 v[104:105], v[104:105], v[0:1] op_sel_hi:[1,0]
	v_pk_mul_f32 v[94:95], v[94:95], v[0:1] op_sel_hi:[1,0]
	v_pk_mul_f32 v[96:97], v[96:97], v[0:1] op_sel_hi:[1,0]
	v_cvt_pk_bf16_f32 v102, v102, v103
	v_cvt_pk_bf16_f32 v103, v104, v105
	v_cvt_pk_bf16_f32 v104, v94, v95
	v_cvt_pk_bf16_f32 v105, v96, v97
	ds_bpermute_b32 v228, v216, v102
	ds_bpermute_b32 v229, v216, v103
	ds_bpermute_b32 v230, v216, v104
	ds_bpermute_b32 v231, v216, v105
	s_waitcnt lgkmcnt(4)
	global_store_dwordx4 v[220:221], v[224:227], off
	v_pk_mul_f32 v[98:99], v[98:99], v[132:133] op_sel_hi:[1,0]
	v_pk_mul_f32 v[100:101], v[100:101], v[132:133] op_sel_hi:[1,0]
	v_pk_mul_f32 v[90:91], v[90:91], v[132:133] op_sel_hi:[1,0]
	v_pk_mul_f32 v[92:93], v[92:93], v[132:133] op_sel_hi:[1,0]
	v_cvt_pk_bf16_f32 v98, v98, v99
	v_cvt_pk_bf16_f32 v99, v100, v101
	v_cvt_pk_bf16_f32 v100, v90, v91
	v_cvt_pk_bf16_f32 v101, v92, v93
	ds_bpermute_b32 v224, v216, v98
	ds_bpermute_b32 v225, v216, v99
	ds_bpermute_b32 v226, v216, v100
	ds_bpermute_b32 v227, v216, v101
	s_waitcnt lgkmcnt(4)
	global_store_dwordx4 v[220:221], v[228:231], off offset:256
	v_lshl_add_u64 v[220:221], v[220:221], 0, s[8:9]
	v_pk_mul_f32 v[86:87], v[86:87], v[132:133] op_sel_hi:[1,0]
	v_pk_mul_f32 v[88:89], v[88:89], v[132:133] op_sel_hi:[1,0]
	v_pk_mul_f32 v[78:79], v[78:79], v[132:133] op_sel_hi:[1,0]
	v_pk_mul_f32 v[80:81], v[80:81], v[132:133] op_sel_hi:[1,0]
	v_cvt_pk_bf16_f32 v86, v86, v87
	v_cvt_pk_bf16_f32 v87, v88, v89
	v_cvt_pk_bf16_f32 v88, v78, v79
	v_cvt_pk_bf16_f32 v89, v80, v81
	ds_bpermute_b32 v228, v216, v86
	ds_bpermute_b32 v229, v216, v87
	ds_bpermute_b32 v230, v216, v88
	ds_bpermute_b32 v231, v216, v89
	s_waitcnt lgkmcnt(4)
	global_store_dwordx4 v[220:221], v[224:227], off
	v_pk_mul_f32 v[82:83], v[82:83], v[142:143] op_sel_hi:[1,0]
	v_pk_mul_f32 v[84:85], v[84:85], v[142:143] op_sel_hi:[1,0]
	v_pk_mul_f32 v[74:75], v[74:75], v[142:143] op_sel_hi:[1,0]
	v_pk_mul_f32 v[76:77], v[76:77], v[142:143] op_sel_hi:[1,0]
	v_cvt_pk_bf16_f32 v82, v82, v83
	v_cvt_pk_bf16_f32 v83, v84, v85
	v_cvt_pk_bf16_f32 v84, v74, v75
	v_cvt_pk_bf16_f32 v85, v76, v77
	ds_bpermute_b32 v224, v216, v82
	ds_bpermute_b32 v225, v216, v83
	ds_bpermute_b32 v226, v216, v84
	ds_bpermute_b32 v227, v216, v85
	s_waitcnt lgkmcnt(4)
	global_store_dwordx4 v[220:221], v[228:231], off offset:256
	v_lshl_add_u64 v[220:221], v[220:221], 0, s[8:9]
	v_pk_mul_f32 v[70:71], v[70:71], v[142:143] op_sel_hi:[1,0]
	v_pk_mul_f32 v[72:73], v[72:73], v[142:143] op_sel_hi:[1,0]
	v_pk_mul_f32 v[66:67], v[66:67], v[142:143] op_sel_hi:[1,0]
	v_pk_mul_f32 v[68:69], v[68:69], v[142:143] op_sel_hi:[1,0]
	v_cvt_pk_bf16_f32 v70, v70, v71
	v_cvt_pk_bf16_f32 v71, v72, v73
	v_cvt_pk_bf16_f32 v72, v66, v67
	v_cvt_pk_bf16_f32 v73, v68, v69
	ds_bpermute_b32 v228, v216, v70
	ds_bpermute_b32 v229, v216, v71
	ds_bpermute_b32 v230, v216, v72
	ds_bpermute_b32 v231, v216, v73
	s_waitcnt lgkmcnt(4)
; __device__ __forceinline__ float sigm(float v) { return __builtin_amdgcn_rcpf(1.0f + __builtin_amdgcn_exp2f(-1.44269504089f * v)); }
; __device__ __forceinline__ u32x4 pack8(const f32x4& v0, const f32x4& v1) { u32x4 w; w.x = cvt_pk_bf16(v0[0], v0[1]); w.y = cvt_pk_bf16(v0[2], v0[3]); w.z = cvt_pk_bf16(v1[0], v1[1]); w.w = cvt_pk_bf16(v1[2], v1[3]); return w; }
; __device__ __forceinline__ float sumsq8(const f32x4& v0, const f32x4& v1) { return (v0[0] * v0[0] + v0[1] * v0[1]) + (v0[2] * v0[2] + v0[3] * v0[3]) + (v1[0] * v1[0] + v1[1] * v1[1]) + (v1[2] * v1[2] + v1[3] * v1[3]); }
; template <int ACT> __device__ __forceinline__ void epi_act_store(f32x4 (&acc)[2][2][4][2], const float (&rs)[2][4], bf16_t* out, int ld, int row0, int col0, float* ssqv_slot, bool want_ssq, int fq) {
;     ...
;         for (int m = 0; m < 4; ++m) { const int row = row0 + ai * 128 + m * 16; float sq = 0.f;
; #pragma unroll
;             for (int bj = 0; bj < 2; ++bj) { f32x4 v0 = acc[ai][bj][m][0] * rs[ai][m], v1 = acc[ai][bj][m][1] * rs[ai][m];
;                 if (ACT == 1) { f32x2 a = gelu_pk((f32x2){v0[0], v0[1]}), b = gelu_pk((f32x2){v0[2], v0[3]}), c = gelu_pk((f32x2){v1[0], v1[1]}), d = gelu_pk((f32x2){v1[2], v1[3]});
;                     v0 = (f32x4){a.x, a.y, b.x, b.y}; v1 = (f32x4){c.x, c.y, d.x, d.y}; sq += sumsq8(v0, v1); }
;                 if (ACT == 2) {
; #pragma unroll
;                     for (int e = 0; e < 4; ++e) { v0[e] = sigm(v0[e]); v1[e] = sigm(v1[e]); } }
;                 *(u32x4*)(out + (size_t)row * ld + col0 + bj * 128) = pack8(v0, v1); }
; __device__ __forceinline__ void epi_run(const Epi& E, f32x4 (&acc)[2][2][4][2], const Unit& u, int wr, int wc, int fr, int fq) {
;     ...
;         if (mode == MODE_UP) { epi_act_store<0>(acc, rs, E.out16, E.ld16, row0, col0, nullptr, false, fq); return; }
	global_store_dwordx4 v[220:221], v[224:227], off
	v_pk_mul_f32 v[62:63], v[62:63], v[140:141] op_sel_hi:[1,0]
	v_pk_mul_f32 v[64:65], v[64:65], v[140:141] op_sel_hi:[1,0]
	v_pk_mul_f32 v[58:59], v[58:59], v[140:141] op_sel_hi:[1,0]
	v_pk_mul_f32 v[60:61], v[60:61], v[140:141] op_sel_hi:[1,0]
	v_cvt_pk_bf16_f32 v62, v62, v63
	v_cvt_pk_bf16_f32 v63, v64, v65
	v_cvt_pk_bf16_f32 v64, v58, v59
	v_cvt_pk_bf16_f32 v65, v60, v61
	ds_bpermute_b32 v224, v216, v62
	ds_bpermute_b32 v225, v216, v63
	ds_bpermute_b32 v226, v216, v64
	ds_bpermute_b32 v227, v216, v65
	s_waitcnt lgkmcnt(4)
	global_store_dwordx4 v[220:221], v[228:231], off offset:256
	v_lshl_add_u64 v[220:221], v[220:221], 0, s[44:45]
	v_pk_mul_f32 v[54:55], v[54:55], v[140:141] op_sel_hi:[1,0]
	v_pk_mul_f32 v[56:57], v[56:57], v[140:141] op_sel_hi:[1,0]
	v_pk_mul_f32 v[50:51], v[50:51], v[140:141] op_sel_hi:[1,0]
	v_pk_mul_f32 v[52:53], v[52:53], v[140:141] op_sel_hi:[1,0]
	v_cvt_pk_bf16_f32 v54, v54, v55
	v_cvt_pk_bf16_f32 v55, v56, v57
	v_cvt_pk_bf16_f32 v56, v50, v51
	v_cvt_pk_bf16_f32 v57, v52, v53
	ds_bpermute_b32 v228, v216, v54
	ds_bpermute_b32 v229, v216, v55
	ds_bpermute_b32 v230, v216, v56
	ds_bpermute_b32 v231, v216, v57
	s_waitcnt lgkmcnt(4)
	global_store_dwordx4 v[220:221], v[224:227], off
	v_pk_mul_f32 v[46:47], v[46:47], v[138:139] op_sel_hi:[1,0]
	v_pk_mul_f32 v[48:49], v[48:49], v[138:139] op_sel_hi:[1,0]
	v_pk_mul_f32 v[42:43], v[42:43], v[138:139] op_sel_hi:[1,0]
	v_pk_mul_f32 v[44:45], v[44:45], v[138:139] op_sel_hi:[1,0]
	v_cvt_pk_bf16_f32 v46, v46, v47
	v_cvt_pk_bf16_f32 v47, v48, v49
	v_cvt_pk_bf16_f32 v48, v42, v43
	v_cvt_pk_bf16_f32 v49, v44, v45
	ds_bpermute_b32 v224, v216, v46
	ds_bpermute_b32 v225, v216, v47
	ds_bpermute_b32 v226, v216, v48
	ds_bpermute_b32 v227, v216, v49
	s_waitcnt lgkmcnt(4)
	global_store_dwordx4 v[220:221], v[228:231], off offset:256
	v_lshl_add_u64 v[220:221], v[220:221], 0, s[8:9]
	v_pk_mul_f32 v[38:39], v[38:39], v[138:139] op_sel_hi:[1,0]
	v_pk_mul_f32 v[40:41], v[40:41], v[138:139] op_sel_hi:[1,0]
	v_pk_mul_f32 v[34:35], v[34:35], v[138:139] op_sel_hi:[1,0]
	v_pk_mul_f32 v[36:37], v[36:37], v[138:139] op_sel_hi:[1,0]
	v_cvt_pk_bf16_f32 v38, v38, v39
	v_cvt_pk_bf16_f32 v39, v40, v41
	v_cvt_pk_bf16_f32 v40, v34, v35
	v_cvt_pk_bf16_f32 v41, v36, v37
	ds_bpermute_b32 v228, v216, v38
	ds_bpermute_b32 v229, v216, v39
	ds_bpermute_b32 v230, v216, v40
	ds_bpermute_b32 v231, v216, v41
	s_waitcnt lgkmcnt(4)
	global_store_dwordx4 v[220:221], v[224:227], off
	v_pk_mul_f32 v[30:31], v[30:31], v[134:135] op_sel_hi:[1,0]
	v_pk_mul_f32 v[32:33], v[32:33], v[134:135] op_sel_hi:[1,0]
	v_pk_mul_f32 v[26:27], v[26:27], v[134:135] op_sel_hi:[1,0]
	v_pk_mul_f32 v[28:29], v[28:29], v[134:135] op_sel_hi:[1,0]
	v_cvt_pk_bf16_f32 v30, v30, v31
	v_cvt_pk_bf16_f32 v31, v32, v33
	v_cvt_pk_bf16_f32 v32, v26, v27
	v_cvt_pk_bf16_f32 v33, v28, v29
	ds_bpermute_b32 v224, v216, v30
	ds_bpermute_b32 v225, v216, v31
	ds_bpermute_b32 v226, v216, v32
	ds_bpermute_b32 v227, v216, v33
	s_waitcnt lgkmcnt(4)
	global_store_dwordx4 v[220:221], v[228:231], off offset:256
	v_lshl_add_u64 v[220:221], v[220:221], 0, s[8:9]
	v_pk_mul_f32 v[22:23], v[22:23], v[134:135] op_sel_hi:[1,0]
	v_pk_mul_f32 v[24:25], v[24:25], v[134:135] op_sel_hi:[1,0]
	v_pk_mul_f32 v[18:19], v[18:19], v[134:135] op_sel_hi:[1,0]
	v_pk_mul_f32 v[20:21], v[20:21], v[134:135] op_sel_hi:[1,0]
	v_cvt_pk_bf16_f32 v22, v22, v23
	v_cvt_pk_bf16_f32 v23, v24, v25
	v_cvt_pk_bf16_f32 v24, v18, v19
	v_cvt_pk_bf16_f32 v25, v20, v21
	ds_bpermute_b32 v228, v216, v22
	ds_bpermute_b32 v229, v216, v23
	ds_bpermute_b32 v230, v216, v24
	ds_bpermute_b32 v231, v216, v25
	s_waitcnt lgkmcnt(4)
	global_store_dwordx4 v[220:221], v[224:227], off
	v_pk_mul_f32 v[14:15], v[14:15], v[136:137] op_sel_hi:[1,0]
	v_pk_mul_f32 v[16:17], v[16:17], v[136:137] op_sel_hi:[1,0]
	v_pk_mul_f32 v[10:11], v[10:11], v[136:137] op_sel_hi:[1,0]
	v_pk_mul_f32 v[12:13], v[12:13], v[136:137] op_sel_hi:[1,0]
	v_cvt_pk_bf16_f32 v14, v14, v15
	v_cvt_pk_bf16_f32 v15, v16, v17
	v_cvt_pk_bf16_f32 v16, v10, v11
	v_cvt_pk_bf16_f32 v17, v12, v13
	ds_bpermute_b32 v224, v216, v14
	ds_bpermute_b32 v225, v216, v15
	ds_bpermute_b32 v226, v216, v16
	ds_bpermute_b32 v227, v216, v17
	s_waitcnt lgkmcnt(4)
	global_store_dwordx4 v[220:221], v[228:231], off offset:256
	v_lshl_add_u64 v[220:221], v[220:221], 0, s[8:9]
	v_pk_mul_f32 v[6:7], v[6:7], v[136:137] op_sel_hi:[1,0]
	v_pk_mul_f32 v[8:9], v[8:9], v[136:137] op_sel_hi:[1,0]
	v_pk_mul_f32 v[2:3], v[2:3], v[136:137] op_sel_hi:[1,0]
	v_pk_mul_f32 v[4:5], v[4:5], v[136:137] op_sel_hi:[1,0]
	v_cvt_pk_bf16_f32 v6, v6, v7
	v_cvt_pk_bf16_f32 v7, v8, v9
	v_cvt_pk_bf16_f32 v8, v2, v3
	v_cvt_pk_bf16_f32 v9, v4, v5
	ds_bpermute_b32 v228, v216, v6
	ds_bpermute_b32 v229, v216, v7
	ds_bpermute_b32 v230, v216, v8
	ds_bpermute_b32 v231, v216, v9
	s_waitcnt lgkmcnt(4)
	global_store_dwordx4 v[220:221], v[224:227], off
	s_waitcnt lgkmcnt(0)
	global_store_dwordx4 v[220:221], v[228:231], off offset:256
